# v102 + ssm chunk recurrence step as two dependent packed f32 fmas (t = -li*xi+zr, li*xr+zi; x = lr*x + t) instead of mul/fma/fma/mov/add: f32 math with fewer roundings, dependent chain two ops deep
# speedup vs baseline: 1.0092x; 1.0002x over previous
; __device__ __forceinline__ void ssm_v2(const KA& A, const Ctx& F, int l, int b, int g) {
;     ...
;     if (w == 0 && (sp_ & 2)) { const float lr = lam[lane], li = lam[64 + lane]; float xr = 0.f, xi = 0.f;
; #pragma unroll 8
;         for (int j = 0; j < 256; ++j) { const float zr = ZF[j * ZS + lane], zi = ZF[j * ZS + 64 + lane];
;             ZF[j * ZS + lane] = xr; ZF[j * ZS + 64 + lane] = xi;
;             const float nr = lr * xr - li * xi + zr, ni = lr * xi + li * xr + zi; xr = nr; xi = ni; } }
.Lssm_rec:
	v_add_u32_e32 v164, 0x1080, v7
	ds_read2st64_b32 v[148:149], v164 offset1:1
	ds_read2_b32 v[150:151], v164 offset0:132 offset1:196
	v_add_u32_e32 v166, 0x20, v164
	ds_read2st64_b32 v[152:153], v166 offset0:4 offset1:5
	v_add_u32_e32 v166, 0x30, v164
	ds_read2st64_b32 v[154:155], v166 offset0:6 offset1:7
	v_add_u32_e32 v166, 0x40, v164
	ds_read2st64_b32 v[156:157], v166 offset0:8 offset1:9
	v_add_u32_e32 v166, 0x50, v164
	ds_read2st64_b32 v[158:159], v166 offset0:10 offset1:11
	v_add_u32_e32 v166, 0x60, v164
	ds_read2st64_b32 v[160:161], v166 offset0:12 offset1:13
	v_add_u32_e32 v166, 0x70, v164
	ds_read2st64_b32 v[162:163], v166 offset0:14 offset1:15
	s_waitcnt lgkmcnt(8)
	ds_write2st64_b32 v7, v4, v5 offset1:1
	v_pk_fma_f32 v[10:11], v[2:3], v[4:5], v[132:133] op_sel:[0,1,0] op_sel_hi:[1,0,1] neg_lo:[1,0,0]
	s_nop 0
	v_pk_fma_f32 v[4:5], v[0:1], v[4:5], v[10:11]
	s_nop 0
	ds_write2_b32 v7, v4, v5 offset0:132 offset1:196
	v_pk_fma_f32 v[10:11], v[2:3], v[4:5], v[134:135] op_sel:[0,1,0] op_sel_hi:[1,0,1] neg_lo:[1,0,0]
	v_add_u32_e32 v165, 0x20, v7
	v_pk_fma_f32 v[4:5], v[0:1], v[4:5], v[10:11]
	s_nop 0
	ds_write2st64_b32 v165, v4, v5 offset0:4 offset1:5
	v_pk_fma_f32 v[10:11], v[2:3], v[4:5], v[136:137] op_sel:[0,1,0] op_sel_hi:[1,0,1] neg_lo:[1,0,0]
	v_add_u32_e32 v165, 0x30, v7
	v_pk_fma_f32 v[4:5], v[0:1], v[4:5], v[10:11]
	s_nop 0
	ds_write2st64_b32 v165, v4, v5 offset0:6 offset1:7
	v_pk_fma_f32 v[10:11], v[2:3], v[4:5], v[138:139] op_sel:[0,1,0] op_sel_hi:[1,0,1] neg_lo:[1,0,0]
	v_add_u32_e32 v165, 0x40, v7
	v_pk_fma_f32 v[4:5], v[0:1], v[4:5], v[10:11]
	s_nop 0
	ds_write2st64_b32 v165, v4, v5 offset0:8 offset1:9
	v_pk_fma_f32 v[10:11], v[2:3], v[4:5], v[140:141] op_sel:[0,1,0] op_sel_hi:[1,0,1] neg_lo:[1,0,0]
	v_add_u32_e32 v165, 0x50, v7
	v_pk_fma_f32 v[4:5], v[0:1], v[4:5], v[10:11]
	s_nop 0
	ds_write2st64_b32 v165, v4, v5 offset0:10 offset1:11
	v_pk_fma_f32 v[10:11], v[2:3], v[4:5], v[142:143] op_sel:[0,1,0] op_sel_hi:[1,0,1] neg_lo:[1,0,0]
	v_add_u32_e32 v165, 0x60, v7
	v_pk_fma_f32 v[4:5], v[0:1], v[4:5], v[10:11]
	s_nop 0
	ds_write2st64_b32 v165, v4, v5 offset0:12 offset1:13
	v_pk_fma_f32 v[10:11], v[2:3], v[4:5], v[144:145] op_sel:[0,1,0] op_sel_hi:[1,0,1] neg_lo:[1,0,0]
	v_add_u32_e32 v165, 0x70, v7
	v_pk_fma_f32 v[4:5], v[0:1], v[4:5], v[10:11]
	s_nop 0
	ds_write2st64_b32 v165, v4, v5 offset0:14 offset1:15
	v_pk_fma_f32 v[10:11], v[2:3], v[4:5], v[146:147] op_sel:[0,1,0] op_sel_hi:[1,0,1] neg_lo:[1,0,0]
	s_nop 0
	v_pk_fma_f32 v[4:5], v[0:1], v[4:5], v[10:11]
	s_nop 0
	v_add_u32_e32 v7, 0x1080, v164
	ds_read2st64_b32 v[132:133], v7 offset1:1
	ds_read2_b32 v[134:135], v7 offset0:132 offset1:196
	v_add_u32_e32 v166, 0x20, v7
	ds_read2st64_b32 v[136:137], v166 offset0:4 offset1:5
	v_add_u32_e32 v166, 0x30, v7
	ds_read2st64_b32 v[138:139], v166 offset0:6 offset1:7
	v_add_u32_e32 v166, 0x40, v7
	ds_read2st64_b32 v[140:141], v166 offset0:8 offset1:9
	v_add_u32_e32 v166, 0x50, v7
	ds_read2st64_b32 v[142:143], v166 offset0:10 offset1:11
	v_add_u32_e32 v166, 0x60, v7
	ds_read2st64_b32 v[144:145], v166 offset0:12 offset1:13
	v_add_u32_e32 v166, 0x70, v7
	ds_read2st64_b32 v[146:147], v166 offset0:14 offset1:15
	s_waitcnt lgkmcnt(8)
	ds_write2st64_b32 v164, v4, v5 offset1:1
	v_pk_fma_f32 v[10:11], v[2:3], v[4:5], v[148:149] op_sel:[0,1,0] op_sel_hi:[1,0,1] neg_lo:[1,0,0]
	s_nop 0
	v_pk_fma_f32 v[4:5], v[0:1], v[4:5], v[10:11]
	s_nop 0
	ds_write2_b32 v164, v4, v5 offset0:132 offset1:196
	v_pk_fma_f32 v[10:11], v[2:3], v[4:5], v[150:151] op_sel:[0,1,0] op_sel_hi:[1,0,1] neg_lo:[1,0,0]
	v_add_u32_e32 v165, 0x20, v164
	v_pk_fma_f32 v[4:5], v[0:1], v[4:5], v[10:11]
	s_nop 0
	ds_write2st64_b32 v165, v4, v5 offset0:4 offset1:5
	v_pk_fma_f32 v[10:11], v[2:3], v[4:5], v[152:153] op_sel:[0,1,0] op_sel_hi:[1,0,1] neg_lo:[1,0,0]
	v_add_u32_e32 v165, 0x30, v164
	v_pk_fma_f32 v[4:5], v[0:1], v[4:5], v[10:11]
	s_nop 0
	ds_write2st64_b32 v165, v4, v5 offset0:6 offset1:7
	v_pk_fma_f32 v[10:11], v[2:3], v[4:5], v[154:155] op_sel:[0,1,0] op_sel_hi:[1,0,1] neg_lo:[1,0,0]
	v_add_u32_e32 v165, 0x40, v164
	v_pk_fma_f32 v[4:5], v[0:1], v[4:5], v[10:11]
	s_nop 0
	ds_write2st64_b32 v165, v4, v5 offset0:8 offset1:9
	v_pk_fma_f32 v[10:11], v[2:3], v[4:5], v[156:157] op_sel:[0,1,0] op_sel_hi:[1,0,1] neg_lo:[1,0,0]
	v_add_u32_e32 v165, 0x50, v164
	v_pk_fma_f32 v[4:5], v[0:1], v[4:5], v[10:11]
	s_nop 0
	ds_write2st64_b32 v165, v4, v5 offset0:10 offset1:11
	v_pk_fma_f32 v[10:11], v[2:3], v[4:5], v[158:159] op_sel:[0,1,0] op_sel_hi:[1,0,1] neg_lo:[1,0,0]
	v_add_u32_e32 v165, 0x60, v164
	v_pk_fma_f32 v[4:5], v[0:1], v[4:5], v[10:11]
	s_nop 0
	ds_write2st64_b32 v165, v4, v5 offset0:12 offset1:13
	v_pk_fma_f32 v[10:11], v[2:3], v[4:5], v[160:161] op_sel:[0,1,0] op_sel_hi:[1,0,1] neg_lo:[1,0,0]
	v_add_u32_e32 v165, 0x70, v164
	v_pk_fma_f32 v[4:5], v[0:1], v[4:5], v[10:11]
	s_nop 0
	ds_write2st64_b32 v165, v4, v5 offset0:14 offset1:15
	v_pk_fma_f32 v[10:11], v[2:3], v[4:5], v[162:163] op_sel:[0,1,0] op_sel_hi:[1,0,1] neg_lo:[1,0,0]
	s_nop 0
	v_pk_fma_f32 v[4:5], v[0:1], v[4:5], v[10:11]
	s_nop 0
	s_addk_i32 s0, 0x2100
	s_cmp_lg_u32 s0, 0x21000
	s_cbranch_scc1 .Lssm_rec
